# dma1: stack4 + attention steady loop: the 3 LDS-DMA tile loads of each step issued after the 4th QK MFMA (earlier by half a QK segment), address temps in free VGPRs
# baseline (speedup 1.0000x reference)
.LBB0_413:
	s_mov_b32 s16, s26
	s_mov_b32 s2, s18
	s_mov_b32 s3, s24
	v_lshl_add_u32 v69, s17, 1, v232
	ds_read_b64_tr_b16 v[76:77], v69 offset:24576
	ds_read_b64_tr_b16 v[78:79], v69 offset:25088
	v_add_f32_e32 v72, v100, v101
	v_add_f32_e32 v72, v102, v72
	v_add_f32_e32 v72, v103, v72
	v_add_f32_e32 v72, v104, v72
	v_add_f32_e32 v72, v105, v72
	v_cvt_pk_bf16_f32 v160, v100, v101
	v_cvt_pk_bf16_f32 v161, v102, v103
	s_waitcnt lgkmcnt(9)
	v_mfma_f32_32x32x16_bf16 v[132:147], v[208:211], v[176:179], 0
	v_add_f32_e32 v72, v106, v72
	v_add_f32_e32 v72, v107, v72
	v_add_f32_e32 v72, v108, v72
	v_add_f32_e32 v72, v109, v72
	v_cvt_pk_bf16_f32 v162, v104, v105
	v_cvt_pk_bf16_f32 v163, v106, v107
	s_waitcnt lgkmcnt(8)
	v_mfma_f32_32x32x16_bf16 v[116:131], v[200:203], v[176:179], 0
	ds_read_b64_tr_b16 v[80:81], v69 offset:25600
	ds_read_b64_tr_b16 v[82:83], v69 offset:26112
	v_add_f32_e32 v72, v110, v72
	v_add_f32_e32 v72, v111, v72
	v_add_f32_e32 v72, v112, v72
	v_add_f32_e32 v72, v113, v72
	v_cvt_pk_bf16_f32 v156, v108, v109
	v_cvt_pk_bf16_f32 v157, v110, v111
	s_waitcnt lgkmcnt(9)
	v_mfma_f32_32x32x16_bf16 v[132:147], v[204:207], v[172:175], v[132:147]
	v_add_f32_e32 v72, v114, v72
	v_add_f32_e32 v72, v115, v72
	v_add_f32_e32 v72, v84, v72
	v_add_f32_e32 v72, v85, v72
	v_cvt_pk_bf16_f32 v158, v112, v113
	v_cvt_pk_bf16_f32 v159, v114, v115
	s_waitcnt lgkmcnt(8)
	v_mfma_f32_32x32x16_bf16 v[116:131], v[196:199], v[172:175], v[116:131]
	v_lshl_add_u64 v[248:249], v[0:1], 0, s[14:15]
	s_add_i32 m0, s24, s0
	v_lshl_add_u64 v[250:251], v[248:249], 0, s[76:77]
	global_load_lds_dwordx4 v[250:251], off
	s_lshl_b32 s17, s26, 1
	s_add_i32 s17, s17, s1
	s_mov_b32 m0, s17
	v_lshl_add_u64 v[254:255], v[70:71], 0, s[14:15]
	v_lshl_add_u64 v[252:253], v[254:255], 0, s[90:91]
	global_load_lds_dwordx4 v[252:253], off
	s_add_i32 m0, s17, 0x2000
	v_lshl_add_u64 v[250:251], v[254:255], 0, s[92:93]
	global_load_lds_dwordx4 v[250:251], off
	ds_read_b64_tr_b16 v[100:101], v69 offset:26624
	ds_read_b64_tr_b16 v[102:103], v69 offset:27136
	v_add_f32_e32 v72, v86, v72
	v_add_f32_e32 v72, v87, v72
	v_add_f32_e32 v72, v88, v72
	v_add_f32_e32 v72, v89, v72
	v_cvt_pk_bf16_f32 v152, v84, v85
	v_cvt_pk_bf16_f32 v153, v86, v87
	s_waitcnt lgkmcnt(9)
	v_mfma_f32_32x32x16_bf16 v[132:147], v[192:195], v[168:171], v[132:147]
	v_add_f32_e32 v72, v90, v72
	v_add_f32_e32 v72, v91, v72
	v_add_f32_e32 v72, v92, v72
	v_add_f32_e32 v72, v93, v72
	v_cvt_pk_bf16_f32 v154, v88, v89
	v_cvt_pk_bf16_f32 v155, v90, v91
	s_waitcnt lgkmcnt(8)
	v_mfma_f32_32x32x16_bf16 v[116:131], v[188:191], v[168:171], v[116:131]
	ds_read_b64_tr_b16 v[84:85], v69 offset:27648
	ds_read_b64_tr_b16 v[86:87], v69 offset:28160
	v_add_f32_e32 v72, v94, v72
	v_add_f32_e32 v72, v95, v72
	v_add_f32_e32 v72, v96, v72
	v_add_f32_e32 v72, v97, v72
	v_cvt_pk_bf16_f32 v148, v92, v93
	v_cvt_pk_bf16_f32 v149, v94, v95
	s_waitcnt lgkmcnt(9)
	v_mfma_f32_32x32x16_bf16 v[132:147], v[184:187], v[164:167], v[132:147]
	v_add_f32_e32 v72, v98, v72
	v_add_f32_e32 v72, v99, v72
	v_add_f32_e32 v72, 0, v72
	v_cvt_pk_bf16_f32 v150, v96, v97
	v_cvt_pk_bf16_f32 v151, v98, v99
	s_waitcnt lgkmcnt(8)
	v_mfma_f32_32x32x16_bf16 v[116:131], v[180:183], v[164:167], v[116:131]
	v_add_f32_e32 v68, v68, v72
	s_waitcnt lgkmcnt(6)
	v_mfma_f32_32x32x16_bf16 v[36:51], v[160:163], v[76:79], v[36:51]
	v_exp_f32_e32 v132, v132
	v_exp_f32_e32 v133, v133
	ds_read_b64_tr_b16 v[76:77], v69 offset:28672
	ds_read_b64_tr_b16 v[78:79], v69 offset:29184
	s_waitcnt lgkmcnt(6)
	v_mfma_f32_32x32x16_bf16 v[36:51], v[156:159], v[80:83], v[36:51]
	v_exp_f32_e32 v134, v134
	v_exp_f32_e32 v135, v135
	ds_read_b64_tr_b16 v[80:81], v69 offset:29696
	ds_read_b64_tr_b16 v[82:83], v69 offset:30208
	s_waitcnt lgkmcnt(6)
	v_mfma_f32_32x32x16_bf16 v[36:51], v[152:155], v[100:103], v[36:51]
	v_exp_f32_e32 v136, v136
	v_exp_f32_e32 v137, v137
	ds_read_b64_tr_b16 v[88:89], v69 offset:30720
	ds_read_b64_tr_b16 v[90:91], v69 offset:31232
	s_waitcnt lgkmcnt(6)
	v_mfma_f32_32x32x16_bf16 v[36:51], v[148:151], v[84:87], v[36:51]
	v_exp_f32_e32 v138, v138
	v_exp_f32_e32 v139, v139
	ds_read_b64_tr_b16 v[84:85], v69 offset:31744
	ds_read_b64_tr_b16 v[86:87], v69 offset:32256
	s_waitcnt lgkmcnt(6)
	v_mfma_f32_32x32x16_bf16 v[52:67], v[160:163], v[76:79], v[52:67]
	v_exp_f32_e32 v140, v140
	v_exp_f32_e32 v141, v141
	ds_read_b64_tr_b16 v[76:77], v69 offset:32768
	ds_read_b64_tr_b16 v[78:79], v69 offset:33280
	s_waitcnt lgkmcnt(6)
	v_mfma_f32_32x32x16_bf16 v[52:67], v[156:159], v[80:83], v[52:67]
	v_exp_f32_e32 v142, v142
	v_exp_f32_e32 v143, v143
	ds_read_b64_tr_b16 v[80:81], v69 offset:33792
	ds_read_b64_tr_b16 v[82:83], v69 offset:34304
	s_waitcnt lgkmcnt(6)
	v_mfma_f32_32x32x16_bf16 v[52:67], v[152:155], v[88:91], v[52:67]
	v_exp_f32_e32 v144, v144
	v_exp_f32_e32 v145, v145
	ds_read_b64_tr_b16 v[88:89], v69 offset:34816
	ds_read_b64_tr_b16 v[90:91], v69 offset:35328
	s_waitcnt lgkmcnt(6)
	v_mfma_f32_32x32x16_bf16 v[52:67], v[148:151], v[84:87], v[52:67]
	v_exp_f32_e32 v146, v146
	v_exp_f32_e32 v147, v147
	ds_read_b64_tr_b16 v[84:85], v69 offset:35840
	ds_read_b64_tr_b16 v[86:87], v69 offset:36352
	s_waitcnt lgkmcnt(6)
	v_mfma_f32_32x32x16_bf16 v[4:19], v[160:163], v[76:79], v[4:19]
	v_exp_f32_e32 v116, v116
	v_exp_f32_e32 v117, v117
	ds_read_b64_tr_b16 v[76:77], v69 offset:36864
	ds_read_b64_tr_b16 v[78:79], v69 offset:37376
	s_waitcnt lgkmcnt(6)
	v_mfma_f32_32x32x16_bf16 v[4:19], v[156:159], v[80:83], v[4:19]
	v_exp_f32_e32 v118, v118
	v_exp_f32_e32 v119, v119
	ds_read_b64_tr_b16 v[80:81], v69 offset:37888
	ds_read_b64_tr_b16 v[82:83], v69 offset:38400
	s_waitcnt lgkmcnt(6)
	v_mfma_f32_32x32x16_bf16 v[4:19], v[152:155], v[88:91], v[4:19]
	v_exp_f32_e32 v120, v120
	v_exp_f32_e32 v121, v121
	ds_read_b64_tr_b16 v[88:89], v69 offset:38912
	ds_read_b64_tr_b16 v[90:91], v69 offset:39424
	s_waitcnt lgkmcnt(6)
	v_mfma_f32_32x32x16_bf16 v[4:19], v[148:151], v[84:87], v[4:19]
	v_exp_f32_e32 v122, v122
	v_exp_f32_e32 v123, v123
	ds_read_b64_tr_b16 v[84:85], v69 offset:39936
	ds_read_b64_tr_b16 v[86:87], v69 offset:40448
	v_add_u32_e32 v69, s16, v230
	ds_read_b128 v[92:95], v69
	ds_read_b128 v[96:99], v69 offset:512
	s_waitcnt lgkmcnt(8)
	v_mfma_f32_32x32x16_bf16 v[20:35], v[160:163], v[76:79], v[20:35]
	v_exp_f32_e32 v124, v124
	v_exp_f32_e32 v125, v125
	ds_read_b128 v[76:79], v69 offset:2048
	ds_read_b128 v[180:183], v69 offset:2560
	s_waitcnt lgkmcnt(8)
	v_mfma_f32_32x32x16_bf16 v[20:35], v[156:159], v[80:83], v[20:35]
	v_exp_f32_e32 v126, v126
	v_exp_f32_e32 v127, v127
	ds_read_b128 v[80:83], v69 offset:4096
	ds_read_b128 v[184:187], v69 offset:4608
	ds_read_b128 v[188:191], v69 offset:6144
	ds_read_b128 v[192:195], v69 offset:6656
	s_waitcnt lgkmcnt(10)
	v_mfma_f32_32x32x16_bf16 v[20:35], v[152:155], v[88:91], v[20:35]
	v_exp_f32_e32 v128, v128
	v_exp_f32_e32 v129, v129
	s_waitcnt lgkmcnt(8)
	v_mfma_f32_32x32x16_bf16 v[20:35], v[148:151], v[84:87], v[20:35]
	v_exp_f32_e32 v130, v130
	v_exp_f32_e32 v131, v131
	s_add_i32 s17, s26, 0x2000
	s_cmpk_lg_i32 s26, 0x4000
	s_cselect_b32 s24, s17, 0
	v_lshl_add_u32 v69, s3, 1, v232
	s_waitcnt vmcnt(3) lgkmcnt(0)
	s_barrier
	ds_read_b64_tr_b16 v[196:197], v69 offset:24576
	ds_read_b64_tr_b16 v[198:199], v69 offset:25088
	s_waitcnt lgkmcnt(9)
	v_mfma_f32_32x32x16_bf16 v[100:115], v[92:95], v[176:179], 0
	v_add_f32_e32 v84, v132, v133
	v_add_f32_e32 v84, v134, v84
	v_add_f32_e32 v84, v135, v84
	v_add_f32_e32 v84, v136, v84
	v_add_f32_e32 v84, v137, v84
	v_cvt_pk_bf16_f32 v160, v132, v133
	v_cvt_pk_bf16_f32 v161, v134, v135
	v_add_f32_e32 v84, v138, v84
	v_add_f32_e32 v84, v139, v84
	v_add_f32_e32 v84, v140, v84
	v_add_f32_e32 v148, v141, v84
	s_waitcnt lgkmcnt(8)
	v_mfma_f32_32x32x16_bf16 v[84:99], v[96:99], v[176:179], 0
	v_cvt_pk_bf16_f32 v162, v136, v137
	v_cvt_pk_bf16_f32 v163, v138, v139
	ds_read_b64_tr_b16 v[132:133], v69 offset:25600
	ds_read_b64_tr_b16 v[134:135], v69 offset:26112
	s_waitcnt lgkmcnt(9)
	v_mfma_f32_32x32x16_bf16 v[100:115], v[76:79], v[172:175], v[100:115]
	v_add_f32_e32 v76, v142, v148
	v_add_f32_e32 v76, v143, v76
	v_add_f32_e32 v76, v144, v76
	v_add_f32_e32 v76, v145, v76
	v_cvt_pk_bf16_f32 v156, v140, v141
	v_cvt_pk_bf16_f32 v157, v142, v143
	s_waitcnt lgkmcnt(8)
	v_mfma_f32_32x32x16_bf16 v[84:99], v[180:183], v[172:175], v[84:99]
	s_add_i32 m0, s26, s0
	v_lshl_add_u64 v[250:251], v[248:249], 0, s[28:29]
	global_load_lds_dwordx4 v[250:251], off
	s_lshl_b32 s3, s24, 1
	s_add_i32 s3, s3, s1
	s_mov_b32 m0, s3
	v_lshl_add_u64 v[252:253], v[254:255], 0, s[66:67]
	global_load_lds_dwordx4 v[252:253], off
	s_add_i32 m0, s3, 0x2000
	v_lshl_add_u64 v[250:251], v[254:255], 0, s[72:73]
	global_load_lds_dwordx4 v[250:251], off
	v_add_f32_e32 v76, v146, v76
	v_add_f32_e32 v76, v147, v76
	v_add_f32_e32 v76, v116, v76
	v_add_f32_e32 v136, v117, v76
	v_cvt_pk_bf16_f32 v158, v144, v145
	v_cvt_pk_bf16_f32 v159, v146, v147
	ds_read_b64_tr_b16 v[76:77], v69 offset:26624
	ds_read_b64_tr_b16 v[78:79], v69 offset:27136
	s_waitcnt lgkmcnt(9)
	v_mfma_f32_32x32x16_bf16 v[100:115], v[80:83], v[168:171], v[100:115]
	v_add_f32_e32 v80, v118, v136
	v_add_f32_e32 v80, v119, v80
	v_add_f32_e32 v80, v120, v80
	v_add_f32_e32 v80, v121, v80
	v_cvt_pk_bf16_f32 v152, v116, v117
	v_cvt_pk_bf16_f32 v153, v118, v119
	s_waitcnt lgkmcnt(8)
	v_mfma_f32_32x32x16_bf16 v[84:99], v[184:187], v[168:171], v[84:99]
	v_add_f32_e32 v80, v122, v80
	v_add_f32_e32 v80, v123, v80
	v_add_f32_e32 v80, v124, v80
	v_add_f32_e32 v116, v125, v80
	v_cvt_pk_bf16_f32 v154, v120, v121
	v_cvt_pk_bf16_f32 v155, v122, v123
	ds_read_b64_tr_b16 v[80:81], v69 offset:27648
	ds_read_b64_tr_b16 v[82:83], v69 offset:28160
	s_waitcnt lgkmcnt(9)
	v_mfma_f32_32x32x16_bf16 v[100:115], v[188:191], v[164:167], v[100:115]
	v_add_f32_e32 v116, v126, v116
	v_add_f32_e32 v116, v127, v116
	v_add_f32_e32 v116, v128, v116
	v_add_f32_e32 v116, v129, v116
	v_cvt_pk_bf16_f32 v148, v124, v125
	v_cvt_pk_bf16_f32 v149, v126, v127
	s_waitcnt lgkmcnt(8)
	v_mfma_f32_32x32x16_bf16 v[84:99], v[192:195], v[164:167], v[84:99]
	v_add_f32_e32 v116, v130, v116
	v_add_f32_e32 v116, v131, v116
	v_add_f32_e32 v116, 0, v116
	v_cvt_pk_bf16_f32 v150, v128, v129
	v_cvt_pk_bf16_f32 v151, v130, v131
	v_add_f32_e32 v68, v68, v116
	s_waitcnt lgkmcnt(6)
	v_mfma_f32_32x32x16_bf16 v[36:51], v[160:163], v[196:199], v[36:51]
	v_exp_f32_e32 v100, v100
	v_exp_f32_e32 v101, v101
	ds_read_b64_tr_b16 v[72:73], v69 offset:28672
	ds_read_b64_tr_b16 v[74:75], v69 offset:29184
	s_waitcnt lgkmcnt(6)
	v_mfma_f32_32x32x16_bf16 v[36:51], v[156:159], v[132:135], v[36:51]
	v_exp_f32_e32 v102, v102
	v_exp_f32_e32 v103, v103
	ds_read_b64_tr_b16 v[116:117], v69 offset:29696
	ds_read_b64_tr_b16 v[118:119], v69 offset:30208
	s_waitcnt lgkmcnt(6)
	v_mfma_f32_32x32x16_bf16 v[36:51], v[152:155], v[76:79], v[36:51]
	v_exp_f32_e32 v104, v104
	v_exp_f32_e32 v105, v105
	ds_read_b64_tr_b16 v[76:77], v69 offset:30720
	ds_read_b64_tr_b16 v[78:79], v69 offset:31232
	s_waitcnt lgkmcnt(6)
	v_mfma_f32_32x32x16_bf16 v[36:51], v[148:151], v[80:83], v[36:51]
	v_exp_f32_e32 v106, v106
	v_exp_f32_e32 v107, v107
	ds_read_b64_tr_b16 v[80:81], v69 offset:31744
	ds_read_b64_tr_b16 v[82:83], v69 offset:32256
	s_waitcnt lgkmcnt(6)
	v_mfma_f32_32x32x16_bf16 v[52:67], v[160:163], v[72:75], v[52:67]
	v_exp_f32_e32 v108, v108
	v_exp_f32_e32 v109, v109
	ds_read_b64_tr_b16 v[72:73], v69 offset:32768
	ds_read_b64_tr_b16 v[74:75], v69 offset:33280
	s_waitcnt lgkmcnt(6)
	v_mfma_f32_32x32x16_bf16 v[52:67], v[156:159], v[116:119], v[52:67]
	v_exp_f32_e32 v110, v110
	v_exp_f32_e32 v111, v111
	ds_read_b64_tr_b16 v[116:117], v69 offset:33792
	ds_read_b64_tr_b16 v[118:119], v69 offset:34304
	s_waitcnt lgkmcnt(6)
	v_mfma_f32_32x32x16_bf16 v[52:67], v[152:155], v[76:79], v[52:67]
	v_exp_f32_e32 v112, v112
	v_exp_f32_e32 v113, v113
	ds_read_b64_tr_b16 v[76:77], v69 offset:34816
	ds_read_b64_tr_b16 v[78:79], v69 offset:35328
	s_waitcnt lgkmcnt(6)
	v_mfma_f32_32x32x16_bf16 v[52:67], v[148:151], v[80:83], v[52:67]
	v_exp_f32_e32 v114, v114
	v_exp_f32_e32 v115, v115
	ds_read_b64_tr_b16 v[80:81], v69 offset:35840
	ds_read_b64_tr_b16 v[82:83], v69 offset:36352
	s_waitcnt lgkmcnt(6)
	v_mfma_f32_32x32x16_bf16 v[4:19], v[160:163], v[72:75], v[4:19]
	v_exp_f32_e32 v84, v84
	v_exp_f32_e32 v85, v85
	ds_read_b64_tr_b16 v[72:73], v69 offset:36864
	ds_read_b64_tr_b16 v[74:75], v69 offset:37376
	s_waitcnt lgkmcnt(6)
	v_mfma_f32_32x32x16_bf16 v[4:19], v[156:159], v[116:119], v[4:19]
	v_exp_f32_e32 v86, v86
	v_exp_f32_e32 v87, v87
	ds_read_b64_tr_b16 v[116:117], v69 offset:37888
	ds_read_b64_tr_b16 v[118:119], v69 offset:38400
	s_waitcnt lgkmcnt(6)
	v_mfma_f32_32x32x16_bf16 v[4:19], v[152:155], v[76:79], v[4:19]
	v_exp_f32_e32 v88, v88
	v_exp_f32_e32 v89, v89
	ds_read_b64_tr_b16 v[76:77], v69 offset:38912
	ds_read_b64_tr_b16 v[78:79], v69 offset:39424
	s_waitcnt lgkmcnt(6)
	v_mfma_f32_32x32x16_bf16 v[4:19], v[148:151], v[80:83], v[4:19]
	v_exp_f32_e32 v90, v90
	v_exp_f32_e32 v91, v91
	ds_read_b64_tr_b16 v[80:81], v69 offset:39936
	ds_read_b64_tr_b16 v[82:83], v69 offset:40448
	v_add_u32_e32 v69, s24, v230
	ds_read_b128 v[208:211], v69
	ds_read_b128 v[200:203], v69 offset:512
	s_waitcnt lgkmcnt(8)
	v_mfma_f32_32x32x16_bf16 v[20:35], v[160:163], v[72:75], v[20:35]
	v_exp_f32_e32 v92, v92
	v_exp_f32_e32 v93, v93
	ds_read_b128 v[204:207], v69 offset:2048
	ds_read_b128 v[196:199], v69 offset:2560
	s_waitcnt lgkmcnt(8)
	v_mfma_f32_32x32x16_bf16 v[20:35], v[156:159], v[116:119], v[20:35]
	v_exp_f32_e32 v94, v94
	v_exp_f32_e32 v95, v95
	ds_read_b128 v[192:195], v69 offset:4096
	ds_read_b128 v[188:191], v69 offset:4608
	ds_read_b128 v[184:187], v69 offset:6144
	ds_read_b128 v[180:183], v69 offset:6656
	s_waitcnt lgkmcnt(10)
	v_mfma_f32_32x32x16_bf16 v[20:35], v[152:155], v[76:79], v[20:35]
	v_exp_f32_e32 v96, v96
	v_exp_f32_e32 v97, v97
	s_waitcnt lgkmcnt(8)
	v_mfma_f32_32x32x16_bf16 v[20:35], v[148:151], v[80:83], v[20:35]
	v_exp_f32_e32 v98, v98
	v_exp_f32_e32 v99, v99
	s_add_i32 s3, s24, 0x2000
	s_cmpk_lg_i32 s24, 0x4000
	s_cselect_b32 s26, s3, 0
	s_add_i32 s18, s2, 2
	s_add_u32 s14, s14, 0x20000
	s_addc_u32 s15, s15, 0
	s_mov_b32 s17, s16
	s_cmp_ge_u32 s18, s21
	s_waitcnt vmcnt(3) lgkmcnt(0)
	s_barrier
	s_cbranch_scc0 .LBB0_413
	s_add_i32 s64, s2, -3
	s_lshl_b64 s[12:13], s[12:13], 9
	s_add_i32 s2, s64, 1
	s_cmp_lt_u32 s2, s21
	s_cbranch_scc0 .LBB0_441
